# g9: g8 + sc1 write-through on P0 converted-weight stores
# baseline (speedup 1.0000x reference)
; #define LAS __attribute__((address_space(3)))
; __device__ __forceinline__ unsigned pk2(float lo, float hi) { return f2bf(lo) | (f2bf(hi) << 16); }
; __global__ void __launch_bounds__(NWAVES * 64, 2) fwd_megakernel(Args args) {
;     ...
;             for (int i = 0; i < 8; ++i) { LAS float* w = scr + (8 * i + (lane >> 3)) * 33 + (lane & 7) * 4; w[0] = cur[i].x; w[1] = cur[i].y; w[2] = cur[i].z; w[3] = cur[i].w; }
;             asm volatile("s_waitcnt lgkmcnt(0)" ::: "memory");
;             f32x4 g0 = {1.f, 1.f, 1.f, 1.f}, g1 = g0;
;             if (A.gk) { g0 = *(const f32x4*)A.gk; g1 = *(const f32x4*)(A.gk + 4); }
; #pragma unroll
;             for (int j = 0; j < 4; ++j) { const LAS float* sp = scr + (8 * (lane & 7)) * 33 + (lane >> 3) + 8 * j;
;                 v4u o; o.x = pk2(sp[0 * 33] * g0.x, sp[1 * 33] * g0.y); o.y = pk2(sp[2 * 33] * g0.z, sp[3 * 33] * g0.w); o.z = pk2(sp[4 * 33] * g1.x, sp[5 * 33] * g1.y); o.w = pk2(sp[6 * 33] * g1.z, sp[7 * 33] * g1.w);
;                 *(v4u*)(A.dst + (size_t)j * 8 * A.K) = o; }
;             asm volatile("s_waitcnt lgkmcnt(0)" ::: "memory");
;             if (hasB) { A = B;
; #pragma unroll
;                 for (int i = 0; i < 8; ++i) cur[i] = nxt[i]; }
.LBB0_20:
	s_or_b64 exec, exec, s[8:9]
	ds_read2_b32 v[8:9], v69 offset1:8
	ds_read2_b32 v[16:17], v69 offset0:66 offset1:74
	ds_read2_b32 v[18:19], v69 offset0:33 offset1:41
	ds_read2_b32 v[20:21], v69 offset0:99 offset1:107
	ds_read2_b32 v[22:23], v69 offset0:132 offset1:140
	ds_read2_b32 v[24:25], v69 offset0:198 offset1:206
	ds_read2_b32 v[26:27], v69 offset0:165 offset1:173
	ds_read2_b32 v[28:29], v69 offset0:231 offset1:239
	s_waitcnt lgkmcnt(0)
	v_mov_b32_e32 v12, v8
	v_mov_b32_e32 v14, v18
	v_mov_b32_e32 v15, v20
	v_mov_b32_e32 v32, v26
	v_mov_b32_e32 v33, v28
	v_mov_b32_e32 v13, v16
	v_pk_mul_f32 v[14:15], v[4:5], v[14:15]
	v_mov_b32_e32 v30, v22
	v_mov_b32_e32 v31, v24
	v_pk_mul_f32 v[32:33], v[10:11], v[32:33]
	v_pk_mul_f32 v[12:13], v[6:7], v[12:13]
	v_pk_mul_f32 v[30:31], v[2:3], v[30:31]
	v_bfe_u32 v16, v32, 16, 1
	v_bfe_u32 v18, v15, 16, 1
	v_bfe_u32 v20, v14, 16, 1
	v_add3_u32 v20, v14, v20, s37
	v_add3_u32 v18, v15, v18, s37
	v_add3_u32 v14, v32, v16, s37
	v_bfe_u32 v15, v12, 16, 1
	v_bfe_u32 v16, v13, 16, 1
	v_bfe_u32 v22, v30, 16, 1
	v_bfe_u32 v24, v31, 16, 1
	v_bfe_u32 v8, v33, 16, 1
	v_add3_u32 v24, v31, v24, s37
	v_add3_u32 v22, v30, v22, s37
	v_add3_u32 v13, v13, v16, s37
	v_add3_u32 v12, v12, v15, s37
	v_add3_u32 v8, v33, v8, s37
	v_lshrrev_b32_e32 v12, 16, v12
	v_lshrrev_b32_e32 v13, 16, v13
	v_lshrrev_b32_e32 v16, 16, v22
	v_lshrrev_b32_e32 v15, 16, v24
	v_and_or_b32 v15, v8, s38, v15
	v_and_or_b32 v14, v14, s38, v16
	v_and_or_b32 v13, v18, s38, v13
	v_and_or_b32 v12, v20, s38, v12
	v_mov_b32_e32 v16, v9
	v_mov_b32_e32 v20, v19
	v_mov_b32_e32 v28, v27
	global_store_dwordx4 v[70:71], v[12:15], off sc1
	v_pk_mul_f32 v[8:9], v[6:7], v[16:17]
	v_mov_b32_e32 v24, v23
	v_pk_mul_f32 v[12:13], v[4:5], v[20:21]
	v_pk_mul_f32 v[16:17], v[10:11], v[28:29]
	v_pk_mul_f32 v[14:15], v[2:3], v[24:25]
	v_bfe_u32 v18, v17, 16, 1
	v_bfe_u32 v19, v16, 16, 1
	v_bfe_u32 v20, v13, 16, 1
	v_bfe_u32 v21, v12, 16, 1
	v_add3_u32 v12, v12, v21, s37
	v_add3_u32 v13, v13, v20, s37
	v_add3_u32 v16, v16, v19, s37
	v_add3_u32 v17, v17, v18, s37
	v_bfe_u32 v18, v8, 16, 1
	v_bfe_u32 v19, v9, 16, 1
	v_bfe_u32 v20, v14, 16, 1
	v_bfe_u32 v21, v15, 16, 1
	s_ashr_i32 s5, s4, 31
	v_add3_u32 v15, v15, v21, s37
	v_add3_u32 v14, v14, v20, s37
	v_add3_u32 v9, v9, v19, s37
	v_add3_u32 v8, v8, v18, s37
	v_lshrrev_b32_e32 v8, 16, v8
	v_lshrrev_b32_e32 v9, 16, v9
	v_lshrrev_b32_e32 v14, 16, v14
	v_lshrrev_b32_e32 v15, 16, v15
	s_lshl_b64 s[4:5], s[4:5], 4
	v_and_or_b32 v15, v17, s38, v15
	v_and_or_b32 v14, v16, s38, v14
	v_and_or_b32 v13, v13, s38, v9
	v_and_or_b32 v12, v12, s38, v8
	v_lshl_add_u64 v[8:9], v[70:71], 0, s[4:5]
	ds_read2_b32 v[16:17], v69 offset0:16 offset1:24
	ds_read2_b32 v[18:19], v69 offset0:82 offset1:90
	global_store_dwordx4 v[8:9], v[12:15], off sc1
	ds_read2_b32 v[20:21], v69 offset0:49 offset1:57
	ds_read2_b32 v[22:23], v69 offset0:115 offset1:123
	ds_read2_b32 v[24:25], v69 offset0:148 offset1:156
	ds_read2_b32 v[26:27], v69 offset0:214 offset1:222
	ds_read2_b32 v[28:29], v69 offset0:181 offset1:189
	ds_read2_b32 v[30:31], v69 offset0:247 offset1:255
	s_waitcnt lgkmcnt(7)
	v_mov_b32_e32 v12, v16
	s_waitcnt lgkmcnt(5)
	v_mov_b32_e32 v14, v20
	s_waitcnt lgkmcnt(4)
	v_mov_b32_e32 v15, v22
	s_waitcnt lgkmcnt(1)
	v_mov_b32_e32 v70, v28
	s_waitcnt lgkmcnt(0)
	v_mov_b32_e32 v71, v30
	v_mov_b32_e32 v13, v18
	v_pk_mul_f32 v[14:15], v[4:5], v[14:15]
	v_pk_mul_f32 v[70:71], v[10:11], v[70:71]
	v_pk_mul_f32 v[12:13], v[6:7], v[12:13]
	v_mov_b32_e32 v32, v24
	v_mov_b32_e32 v33, v26
	v_bfe_u32 v16, v71, 16, 1
	v_bfe_u32 v20, v15, 16, 1
	v_pk_mul_f32 v[32:33], v[2:3], v[32:33]
	v_bfe_u32 v18, v70, 16, 1
	v_bfe_u32 v22, v14, 16, 1
	v_add3_u32 v20, v15, v20, s37
	v_add3_u32 v15, v71, v16, s37
	v_bfe_u32 v16, v12, 16, 1
	v_add3_u32 v22, v14, v22, s37
	v_add3_u32 v14, v70, v18, s37
	v_bfe_u32 v18, v13, 16, 1
	v_bfe_u32 v24, v32, 16, 1
	v_bfe_u32 v26, v33, 16, 1
	v_add3_u32 v12, v12, v16, s37
	v_add3_u32 v26, v33, v26, s37
	v_add3_u32 v24, v32, v24, s37
	v_add3_u32 v13, v13, v18, s37
	v_lshrrev_b32_e32 v12, 16, v12
	v_lshrrev_b32_e32 v13, 16, v13
	v_lshrrev_b32_e32 v16, 16, v24
	v_lshrrev_b32_e32 v18, 16, v26
	v_and_or_b32 v12, v22, s38, v12
	v_mov_b32_e32 v22, v21
	v_mov_b32_e32 v30, v29
	v_and_or_b32 v15, v15, s38, v18
	v_and_or_b32 v14, v14, s38, v16
	v_and_or_b32 v13, v20, s38, v13
	v_lshl_add_u64 v[8:9], v[8:9], 0, s[4:5]
	v_mov_b32_e32 v18, v17
	v_pk_mul_f32 v[4:5], v[4:5], v[22:23]
	v_mov_b32_e32 v26, v25
	v_pk_mul_f32 v[10:11], v[10:11], v[30:31]
	global_store_dwordx4 v[8:9], v[12:15], off sc1
	v_pk_mul_f32 v[6:7], v[6:7], v[18:19]
	v_pk_mul_f32 v[2:3], v[2:3], v[26:27]
	v_bfe_u32 v12, v11, 16, 1
	v_bfe_u32 v13, v10, 16, 1
	v_bfe_u32 v14, v5, 16, 1
	v_bfe_u32 v15, v4, 16, 1
	v_add3_u32 v15, v4, v15, s37
	v_add3_u32 v14, v5, v14, s37
	v_add3_u32 v4, v10, v13, s37
	v_add3_u32 v5, v11, v12, s37
	v_bfe_u32 v10, v6, 16, 1
	v_bfe_u32 v11, v7, 16, 1
	v_bfe_u32 v12, v2, 16, 1
	v_bfe_u32 v13, v3, 16, 1
	v_add3_u32 v3, v3, v13, s37
	v_add3_u32 v2, v2, v12, s37
	v_add3_u32 v7, v7, v11, s37
	v_add3_u32 v6, v6, v10, s37
	v_lshrrev_b32_e32 v6, 16, v6
	v_lshrrev_b32_e32 v7, 16, v7
	v_lshrrev_b32_e32 v2, 16, v2
	v_lshrrev_b32_e32 v3, 16, v3
	v_and_or_b32 v5, v5, s38, v3
	v_and_or_b32 v4, v4, s38, v2
	v_and_or_b32 v3, v14, s38, v7
	v_and_or_b32 v2, v15, s38, v6
	v_lshl_add_u64 v[6:7], v[8:9], 0, s[4:5]
	global_store_dwordx4 v[6:7], v[2:5], off sc1
	s_waitcnt lgkmcnt(0)
	s_add_i32 s21, s21, s23
	s_and_b64 vcc, exec, s[6:7]
	s_mov_b32 s4, s40
	v_mov_b64_e32 v[70:71], v[76:77]
	v_mov_b64_e32 v[72:73], v[74:75]
	v_mov_b32_e32 v2, v34
	v_mov_b32_e32 v3, v35
	v_mov_b32_e32 v4, v36
	v_mov_b32_e32 v5, v37
	v_mov_b32_e32 v6, v38
	v_mov_b32_e32 v7, v39
	v_mov_b32_e32 v8, v40
	v_mov_b32_e32 v9, v41
	v_mov_b32_e32 v10, v42
	v_mov_b32_e32 v11, v43
	v_mov_b32_e32 v12, v44
	v_mov_b32_e32 v13, v45
	v_mov_b32_e32 v14, v46
	v_mov_b32_e32 v15, v47
	v_mov_b32_e32 v16, v48
	v_mov_b32_e32 v17, v49
	v_mov_b32_e32 v18, v50
	v_mov_b32_e32 v19, v51
	v_mov_b32_e32 v20, v52
	v_mov_b32_e32 v21, v53
	v_mov_b32_e32 v22, v54
	v_mov_b32_e32 v23, v55
	v_mov_b32_e32 v24, v56
	v_mov_b32_e32 v25, v57
	v_mov_b32_e32 v26, v58
	v_mov_b32_e32 v27, v59
	v_mov_b32_e32 v28, v60
	v_mov_b32_e32 v29, v61
	v_mov_b32_e32 v30, v62
	v_mov_b32_e32 v31, v63
	v_mov_b32_e32 v32, v64
	v_mov_b32_e32 v33, v65
	s_cbranch_vccnz .LBB0_43
